# v4 + mixer-B rpb table load overlapped with the unit Q/K/V prologue loads
# speedup vs baseline: 1.0020x; 1.0020x over previous
; #define LAS __attribute__((address_space(3)))
; #define ATT_SEQ_ROW(i) ((i) < nmask ? lbase + 64 * ATT_SEQ_TL(i) : ((i) - nmask < nl1 ? lbase + 64 * (tlu0 + (i) - nmask) : crow0 + 64 * ((i) - nmask - nl1)))
; template <int MODE, bool FIX> ...
;     ...
;         LAS float* rt = (LAS float*)(lds + RPB_OFF);
;         if (tid < 465) rt[tid] = rpb[head * 465 + tid] * LOG2E;
;     }
;     const int NT = NTL + 4, crow0 = ML + b * CTXL;
;     const LAS float* rpbl = (const LAS float*)(lds + RPB_OFF);
;     bf16x8 qf[4];
;     { const bf16_t* qp = QKV + (size_t)(b * SEQ + qtok) * INC + qcol + hi * 8;
; #pragma unroll
;       for (int d0 = 0; d0 < 4; ++d0) qf[d0] = *(const bf16x8*)(qp + d0 * 16); }
;     ...
;         u32x4 kA, vA;
;         { const size_t ro_ = (size_t)ATT_SEQ_ROW(0) * INC; kA = *(const u32x4*)(gk + ro_); vA = *(const u32x4*)(gv + ro_); }
.LBB0_722:
	s_and_b64 vcc, exec, s[8:9]
	s_cbranch_vccz .LBB0_676
	s_bfe_u32 s53, s15, 0x30004
	s_and_saveexec_b64 s[8:9], s[6:7]
	s_cbranch_execz .LBB0_725
	s_mul_i32 s10, s53, 0x1d1
	v_add_u32_e32 v2, s10, v188
	v_readlane_b32 s10, v255, 7
	v_ashrrev_i32_e32 v3, 31, v2
	v_readlane_b32 s11, v255, 8
	s_nop 1
	v_lshl_add_u64 v[2:3], v[2:3], 2, s[10:11]
	global_load_dword v242, v[2:3], off
.LBB0_725:
	s_or_b64 exec, exec, s[8:9]
	s_ashr_i32 s8, s15, 7
	s_lshl_b32 s51, s8, 12
	s_lshl_b32 s52, s8, 8
	v_readlane_b32 s8, v255, 20
	v_or_b32_e32 v0, s51, v149
	v_readlane_b32 s9, v255, 21
	v_add_u32_e32 v14, v0, v159
	s_add_i32 s52, s52, 0x8000
	v_mov_b64_e32 v[2:3], s[8:9]
	v_mad_i64_i32 v[2:3], s[8:9], v14, s2, v[2:3]
	s_lshl_b32 s8, s50, 6
	s_or_b32 s10, s16, s51
	s_lshl_b32 s42, s53, 7
	s_add_i32 s11, s8, s52
	s_cmp_lt_i32 s49, 0
	v_lshl_add_u64 v[2:3], v[2:3], 0, s[42:43]
	s_cselect_b64 s[8:9], -1, 0
	v_lshl_add_u64 v[32:33], v[176:177], 1, v[2:3]
	s_and_b64 vcc, s[8:9], exec
	global_load_dwordx4 v[2:5], v[32:33], off offset:1536
	global_load_dwordx4 v[6:9], v[32:33], off offset:1568
	global_load_dwordx4 v[10:13], v[32:33], off offset:1600
	global_load_dwordx4 v[92:95], v[32:33], off offset:1632
	v_lshl_add_u64 v[104:105], v[180:181], 0, s[42:43]
	s_cselect_b32 s8, s11, s10
	v_mad_i64_i32 v[32:33], s[8:9], s8, v156, v[104:105]
	global_load_dwordx4 v[96:99], v[32:33], off offset:2560
	global_load_dwordx4 v[100:103], v[32:33], off offset:3584
	s_waitcnt vmcnt(6)
	v_mul_f32_e32 v242, 0x3fb8aa3b, v242
	ds_write_b32 v151, v242
	s_mov_b32 s11, 0
	s_mov_b32 s10, 0
	s_cbranch_vccnz .LBB0_729
	v_sub_co_u32_e64 v0, s[8:9], s13, 3
	v_add_u32_e32 v15, -4, v158
	v_min_u32_e32 v0, 56, v0
	v_min_u32_e32 v15, 56, v15
	v_sub_co_u32_e64 v32, s[16:17], s13, 4
	s_cmp_gt_u32 s13, 3
	v_add_u32_e32 v0, 7, v0
	v_cndmask_b32_e64 v33, v15, 0, s[16:17]
	s_cselect_b64 s[44:45], -1, 0
	v_cndmask_b32_e64 v80, v0, 7, s[8:9]
	s_min_u32 s8, s12, 4
	v_sub_u32_e32 v0, s12, v33
	s_add_i32 s9, s14, s8
	v_subrev_u32_e32 v81, s8, v0
	v_add_u32_e32 v0, s8, v148
	s_sub_i32 s42, s9, s12
	s_sub_i32 s9, s12, s14
	v_mad_i32_i24 v82, v0, s3, v155
	v_mov_b32_e32 v0, 0
	v_min_u32_e32 v15, 56, v32
	s_add_i32 s42, s42, 1
	s_sub_i32 s54, s9, s8
	v_mov_b32_e32 v32, 0
	v_mov_b32_e32 v33, v0
	v_mov_b32_e32 v34, v0
	v_mov_b32_e32 v35, v0
	v_mov_b32_e32 v36, v0
	v_mov_b32_e32 v37, v0
	v_mov_b32_e32 v38, v0
	v_mov_b32_e32 v39, v0
	v_mov_b32_e32 v40, v0
	v_mov_b32_e32 v41, v0
	v_mov_b32_e32 v42, v0
	v_mov_b32_e32 v43, v0
	v_mov_b32_e32 v44, v0
	v_mov_b32_e32 v45, v0
	v_mov_b32_e32 v46, v0
	v_mov_b32_e32 v47, v0
	v_mov_b32_e32 v48, 0
	v_mov_b32_e32 v49, v0
	v_mov_b32_e32 v50, v0
	v_mov_b32_e32 v51, v0
	v_mov_b32_e32 v52, v0
	v_mov_b32_e32 v53, v0
	v_mov_b32_e32 v54, v0
	v_mov_b32_e32 v55, v0
	v_mov_b32_e32 v56, v0
	v_mov_b32_e32 v57, v0
	v_mov_b32_e32 v58, v0
	v_mov_b32_e32 v59, v0
	v_mov_b32_e32 v60, v0
	v_mov_b32_e32 v61, v0
	v_mov_b32_e32 v62, v0
	v_mov_b32_e32 v63, v0
